# window-attention softmax: conservative post-inline-asm s_nop pads removed from the v_max3 chains
# speedup vs baseline: 1.0154x; 1.0064x over previous
; #define LAS3 __attribute__((address_space(3)))
; __device__ __forceinline__ int crow(int r, int hi) { return (r & 3) + 8 * (r >> 2) + 4 * hi; }
; __device__ __forceinline__ float max2f(float a, float b) { float r; asm("v_max_f32_e32 %0, %1, %2" : "=v"(r) : "v"(a), "v"(b)); return r; }
; __device__ __forceinline__ float max3f(float a, float b, float c) { float r; asm("v_max3_f32 %0, %1, %2, %3" : "=v"(r) : "v"(a), "v"(b), "v"(c)); return r; }
; template <int MODE>
; __device__ __forceinline__ void attn_unit(const Tensors& T0, int ureq, int b, int hh, int qblk, LAS3 char* shm, const bool dummy = false) {
;     ...
;     if (near) {
;       const LAS3 float* tp = tab + (MODE ? 0 : sub * TABW) + (k0 - q0w - r32 + 4 * hi + TAB0);
; #pragma unroll
;       for (int r = 0; r < 16; ++r) { C0[r] += tp[(r & 3) + 8 * (r >> 2)]; C1[r] += tp[(r & 3) + 8 * (r >> 2) + 32]; }
;     }
;     float rm;
;     { float a = max3f(C0[0], C0[1], C1[0]), bq = max3f(C0[2], C0[3], C1[1]); a = max3f(a, C1[2], C1[3]);
; #pragma unroll
;       for (int r = 4; r < 16; r += 4) { a = max3f(a, C0[r], C0[r + 1]); bq = max3f(bq, C0[r + 2], C0[r + 3]); a = max3f(a, C1[r], C1[r + 1]); bq = max3f(bq, C1[r + 2], C1[r + 3]); }
;       a = max2f(a, bq);
;       auto rr = __builtin_amdgcn_permlane32_swap(__float_as_uint(a), __float_as_uint(a), false, false);
;       rm = max2f(__uint_as_float(rr[0]), __uint_as_float(rr[1])); }
;     if (first || __any(rm > THRL)) {
;       const float dl = first ? rm : __builtin_fmaxf(rm, 0.f);
;       mhat += dl;
; #pragma unroll
;       for (int r = 0; r < 16; ++r) { C0[r] -= dl; C1[r] -= dl; negm[r] = curcb - mhat; }
;       if (!first) {
;         const float f = __builtin_amdgcn_exp2f(-dl); l_reg *= f;
;         if (hi == 0) wsf[r32] = f;
;         asm volatile("s_waitcnt lgkmcnt(0)" ::: "memory");
; #pragma unroll
;         for (int r = 0; r < 16; ++r) { const float fr_ = wsf[crow(r, hi)];
; #pragma unroll
;           for (int d = 0; d < ND; ++d) o[d][r] *= fr_; }
;       }
.LBB0_173:
	s_mul_i32 s44, s84, 0x900
	v_or_b32_e32 v49, s85, v123
	s_lshl_b32 s19, s68, 6
	s_add_i32 s18, s44, 0
	v_sub_u32_e32 v49, s19, v49
	s_add_i32 s18, s18, 0x20800
	v_lshlrev_b32_e32 v82, 2, v124
	v_lshlrev_b32_e32 v49, 2, v49
	v_add3_u32 v49, s18, v82, v49
	v_add_u32_e32 v82, 0x480, v49
	v_add_u32_e32 v84, 0x500, v49
	v_add_u32_e32 v86, 0x488, v49
	ds_read2_b32 v[82:83], v82 offset1:1
	ds_read2_b32 v[84:85], v84 offset1:1
	ds_read2_b32 v[86:87], v86 offset1:1
	v_add_u32_e32 v88, 0x508, v49
	v_add_u32_e32 v92, 0x528, v49
	s_waitcnt lgkmcnt(2)
	v_add_f32_e32 v66, v66, v82
	v_add_f32_e32 v67, v67, v83
	s_waitcnt lgkmcnt(1)
	v_add_f32_e32 v82, v50, v84
	v_add_f32_e32 v83, v51, v85
	s_waitcnt lgkmcnt(0)
	v_add_f32_e32 v50, v68, v86
	v_add_f32_e32 v51, v69, v87
	v_add_u32_e32 v68, 0x4a0, v49
	ds_read2_b32 v[88:89], v88 offset1:1
	v_add_u32_e32 v84, 0x520, v49
	v_add_u32_e32 v85, 0x4a8, v49
	ds_read2_b32 v[68:69], v68 offset1:1
	ds_read2_b32 v[86:87], v84 offset1:1
	ds_read2_b32 v[90:91], v85 offset1:1
	ds_read2_b32 v[92:93], v92 offset1:1
	v_lshl_add_u32 v132, v123, 2, s69
	s_waitcnt lgkmcnt(3)
	v_add_f32_e32 v68, v70, v68
	v_add_f32_e32 v69, v71, v69
	s_waitcnt lgkmcnt(2)
	v_add_f32_e32 v70, v54, v86
	v_add_f32_e32 v71, v55, v87
	v_add_f32_e32 v84, v52, v88
	v_add_f32_e32 v85, v53, v89
	s_waitcnt lgkmcnt(0)
	v_add_f32_e32 v54, v56, v92
	v_add_f32_e32 v55, v57, v93
	v_add_u32_e32 v56, 0x4c0, v49
	v_add_f32_e32 v52, v72, v90
	v_add_f32_e32 v53, v73, v91
	v_add_u32_e32 v72, 0x540, v49
	v_add_u32_e32 v73, 0x4c8, v49
	ds_read2_b32 v[56:57], v56 offset1:1
	ds_read2_b32 v[86:87], v72 offset1:1
	ds_read2_b32 v[88:89], v73 offset1:1
	v_add_u32_e32 v72, 0x548, v49
	ds_read2_b32 v[90:91], v72 offset1:1
	s_waitcnt lgkmcnt(3)
	v_add_f32_e32 v72, v74, v56
	v_add_f32_e32 v73, v75, v57
	s_waitcnt lgkmcnt(2)
	v_add_f32_e32 v74, v58, v86
	v_add_f32_e32 v75, v59, v87
	v_add_u32_e32 v58, 0x4e0, v49
	s_waitcnt lgkmcnt(1)
	v_add_f32_e32 v56, v76, v88
	v_add_f32_e32 v57, v77, v89
	v_add_u32_e32 v76, 0x560, v49
	v_add_u32_e32 v77, 0x4e8, v49
	v_add_u32_e32 v49, 0x568, v49
	ds_read2_b32 v[58:59], v58 offset1:1
	ds_read2_b32 v[88:89], v76 offset1:1
	ds_read2_b32 v[92:93], v77 offset1:1
	ds_read2_b32 v[94:95], v49 offset1:1
	v_max3_f32 v49, v66, v67, v82
	s_waitcnt lgkmcnt(4)
	v_add_f32_e32 v86, v60, v90
	v_add_f32_e32 v87, v61, v91
	v_max3_f32 v49, v49, v84, v85
	s_waitcnt lgkmcnt(3)
	v_add_f32_e32 v76, v78, v58
	v_add_f32_e32 v77, v79, v59
	s_waitcnt lgkmcnt(0)
	v_add_f32_e32 v60, v64, v94
	v_add_f32_e32 v61, v65, v95
	v_max3_f32 v64, v50, v51, v83
	v_max3_f32 v49, v49, v68, v69
	v_add_f32_e32 v58, v80, v92
	v_add_f32_e32 v59, v81, v93
	v_max3_f32 v64, v64, v52, v53
	v_max3_f32 v49, v49, v70, v71
	v_add_f32_e32 v62, v62, v88
	v_add_f32_e32 v63, v63, v89
	v_max3_f32 v64, v64, v54, v55
	v_max3_f32 v49, v49, v72, v73
	v_max3_f32 v64, v64, v56, v57
	v_max3_f32 v49, v49, v74, v75
	v_max3_f32 v64, v64, v86, v87
	v_max3_f32 v49, v49, v76, v77
	v_max3_f32 v64, v64, v58, v59
	v_max3_f32 v49, v49, v62, v63
	v_max3_f32 v64, v64, v60, v61
	v_max_f32_e32 v49, v49, v64
	s_nop 0
	v_mov_b32_e32 v64, v49
	s_nop 1
	v_permlane32_swap_b32_e32 v49, v64
	v_max_f32_e32 v49, v49, v64
	s_nop 0
	v_cmp_lt_f32_e32 vcc, s78, v49
	s_cbranch_vccz .LBB0_177
	v_max_f32_e32 v48, v49, v49
	v_max_f32_e32 v49, 0, v48
	v_exp_f32_e64 v64, -v49
	s_and_saveexec_b64 s[40:41], s[4:5]
	ds_write_b32 v132, v64
	s_or_b64 exec, exec, s[40:41]
	s_waitcnt lgkmcnt(0)
	v_lshl_add_u32 v65, v124, 2, s69
	ds_read_b128 v[78:81], v65 offset:64
	ds_read_b128 v[88:91], v65 offset:96
	ds_read_b128 v[92:95], v65
	ds_read_b128 v[108:111], v65 offset:32
	v_add_f32_e32 v131, v131, v49
	v_sub_f32_e32 v48, 0, v131
	v_sub_f32_e32 v66, v66, v49
	v_sub_f32_e32 v67, v67, v49
	v_sub_f32_e32 v50, v50, v49
	v_sub_f32_e32 v51, v51, v49
	v_sub_f32_e32 v68, v68, v49
	v_sub_f32_e32 v69, v69, v49
	v_sub_f32_e32 v52, v52, v49
	v_sub_f32_e32 v53, v53, v49
	v_sub_f32_e32 v72, v72, v49
	v_sub_f32_e32 v73, v73, v49
	v_sub_f32_e32 v56, v56, v49
	v_sub_f32_e32 v57, v57, v49
	v_sub_f32_e32 v76, v76, v49
	v_sub_f32_e32 v77, v77, v49
	v_sub_f32_e32 v58, v58, v49
	v_sub_f32_e32 v59, v59, v49
	v_sub_f32_e32 v82, v82, v49
	v_sub_f32_e32 v83, v83, v49
	v_sub_f32_e32 v84, v84, v49
	v_sub_f32_e32 v85, v85, v49
	v_sub_f32_e32 v70, v70, v49
	v_sub_f32_e32 v71, v71, v49
	v_sub_f32_e32 v54, v54, v49
	v_sub_f32_e32 v55, v55, v49
	v_sub_f32_e32 v74, v74, v49
	v_sub_f32_e32 v75, v75, v49
	v_sub_f32_e32 v86, v86, v49
	v_sub_f32_e32 v87, v87, v49
	v_sub_f32_e32 v62, v62, v49
	v_sub_f32_e32 v63, v63, v49
	v_sub_f32_e32 v60, v60, v49
	v_sub_f32_e32 v61, v61, v49
	v_mul_f32_e32 v125, v125, v64
	s_waitcnt lgkmcnt(2)
	v_pk_mul_f32 v[46:47], v[46:47], v[90:91]
	v_pk_mul_f32 v[42:43], v[42:43], v[80:81]
	s_waitcnt lgkmcnt(0)
	v_pk_mul_f32 v[38:39], v[38:39], v[110:111]
	v_pk_mul_f32 v[34:35], v[34:35], v[94:95]
	v_pk_mul_f32 v[44:45], v[44:45], v[88:89]
	v_pk_mul_f32 v[40:41], v[40:41], v[78:79]
	v_pk_mul_f32 v[36:37], v[36:37], v[108:109]
	v_pk_mul_f32 v[32:33], v[32:33], v[92:93]
	v_pk_mul_f32 v[30:31], v[30:31], v[90:91]
	v_pk_mul_f32 v[26:27], v[26:27], v[80:81]
	v_pk_mul_f32 v[22:23], v[22:23], v[110:111]
	v_pk_mul_f32 v[18:19], v[18:19], v[94:95]
	v_pk_mul_f32 v[28:29], v[28:29], v[88:89]
	v_pk_mul_f32 v[24:25], v[24:25], v[78:79]
	v_pk_mul_f32 v[20:21], v[20:21], v[108:109]
	v_pk_mul_f32 v[16:17], v[16:17], v[92:93]

; #define LAS3 __attribute__((address_space(3)))
; __device__ __forceinline__ int crow(int r, int hi) { return (r & 3) + 8 * (r >> 2) + 4 * hi; }
; __device__ __forceinline__ float max2f(float a, float b) { float r; asm("v_max_f32_e32 %0, %1, %2" : "=v"(r) : "v"(a), "v"(b)); return r; }
; __device__ __forceinline__ float max3f(float a, float b, float c) { float r; asm("v_max3_f32 %0, %1, %2, %3" : "=v"(r) : "v"(a), "v"(b), "v"(c)); return r; }
; template <int MODE>
; __device__ __forceinline__ void attn_unit(const Tensors& T0, int ureq, int b, int hh, int qblk, LAS3 char* shm, const bool dummy = false) {
;     ...
;     if (near) {
;       const LAS3 float* tp = tab + (MODE ? 0 : sub * TABW) + (k0 - q0w - r32 + 4 * hi + TAB0);
; #pragma unroll
;       for (int r = 0; r < 16; ++r) { C0[r] += tp[(r & 3) + 8 * (r >> 2)]; C1[r] += tp[(r & 3) + 8 * (r >> 2) + 32]; }
;     }
;     float rm;
;     { float a = max3f(C0[0], C0[1], C1[0]), bq = max3f(C0[2], C0[3], C1[1]); a = max3f(a, C1[2], C1[3]);
; #pragma unroll
;       for (int r = 4; r < 16; r += 4) { a = max3f(a, C0[r], C0[r + 1]); bq = max3f(bq, C0[r + 2], C0[r + 3]); a = max3f(a, C1[r], C1[r + 1]); bq = max3f(bq, C1[r + 2], C1[r + 3]); }
;       a = max2f(a, bq);
;       auto rr = __builtin_amdgcn_permlane32_swap(__float_as_uint(a), __float_as_uint(a), false, false);
;       rm = max2f(__uint_as_float(rr[0]), __uint_as_float(rr[1])); }
;     if (first || __any(rm > THRL)) {
;       const float dl = first ? rm : __builtin_fmaxf(rm, 0.f);
;       mhat += dl;
; #pragma unroll
;       for (int r = 0; r < 16; ++r) { C0[r] -= dl; C1[r] -= dl; negm[r] = curcb - mhat; }
;       if (!first) {
;         const float f = __builtin_amdgcn_exp2f(-dl); l_reg *= f;
;         if (hi == 0) wsf[r32] = f;
;         asm volatile("s_waitcnt lgkmcnt(0)" ::: "memory");
; #pragma unroll
;         for (int r = 0; r < 16; ++r) { const float fr_ = wsf[crow(r, hi)];
; #pragma unroll
;           for (int d = 0; d < ND; ++d) o[d][r] *= fr_; }
;       }
.LBB0_205:
	ds_read2_b32 v[108:109], v134 offset1:1
	ds_read2_b32 v[110:111], v134 offset0:32 offset1:33
	ds_read2_b32 v[114:115], v134 offset0:2 offset1:3
	ds_read2_b32 v[118:119], v134 offset0:8 offset1:9
	ds_read2_b32 v[136:137], v134 offset0:10 offset1:11
	s_waitcnt lgkmcnt(4)
	v_add_f32_e32 v112, v80, v108
	v_add_f32_e32 v113, v81, v109
	ds_read2_b32 v[80:81], v134 offset0:34 offset1:35
	ds_read2_b32 v[138:139], v134 offset0:40 offset1:41
	ds_read2_b32 v[140:141], v134 offset0:42 offset1:43
	s_waitcnt lgkmcnt(6)
	v_add_f32_e32 v116, v64, v110
	v_add_f32_e32 v117, v65, v111
	s_waitcnt lgkmcnt(5)
	v_add_f32_e32 v108, v82, v114
	v_add_f32_e32 v109, v83, v115
	s_waitcnt lgkmcnt(2)
	v_add_f32_e32 v110, v66, v80
	v_add_f32_e32 v111, v67, v81
	v_add_f32_e32 v80, v84, v118
	v_add_f32_e32 v81, v85, v119
	s_waitcnt lgkmcnt(1)
	v_add_f32_e32 v82, v68, v138
	v_add_f32_e32 v83, v69, v139
	v_add_f32_e32 v68, v86, v136
	v_add_f32_e32 v69, v87, v137
	ds_read2_b32 v[64:65], v134 offset0:16 offset1:17
	ds_read2_b32 v[66:67], v134 offset0:48 offset1:49
	ds_read2_b32 v[84:85], v134 offset0:18 offset1:19
	ds_read2_b32 v[118:119], v134 offset0:24 offset1:25
	ds_read2_b32 v[136:137], v134 offset0:26 offset1:27
	s_waitcnt lgkmcnt(5)
	v_add_f32_e32 v70, v70, v140
	v_add_f32_e32 v71, v71, v141
	s_waitcnt lgkmcnt(4)
	v_add_f32_e32 v88, v88, v64
	v_add_f32_e32 v89, v89, v65
	ds_read2_b32 v[64:65], v134 offset0:50 offset1:51
	ds_read2_b32 v[138:139], v134 offset0:56 offset1:57
	ds_read2_b32 v[140:141], v134 offset0:58 offset1:59
	s_waitcnt lgkmcnt(5)
	v_add_f32_e32 v84, v90, v84
	v_add_f32_e32 v85, v91, v85
	v_add_f32_e32 v114, v72, v66
	v_add_f32_e32 v115, v73, v67
	s_waitcnt lgkmcnt(2)
	v_add_f32_e32 v86, v74, v64
	v_add_f32_e32 v87, v75, v65
	s_waitcnt lgkmcnt(1)
	v_add_f32_e32 v74, v76, v138
	v_add_f32_e32 v75, v77, v139
	v_max3_f32 v76, v112, v113, v116
	v_max3_f32 v77, v108, v109, v117
	v_add_f32_e32 v72, v92, v118
	v_add_f32_e32 v73, v93, v119
	v_max3_f32 v76, v76, v110, v111
	v_max3_f32 v77, v77, v68, v69
	v_add_f32_e32 v64, v94, v136
	v_add_f32_e32 v65, v95, v137
	v_max3_f32 v76, v76, v80, v81
	v_max3_f32 v77, v77, v70, v71
	s_waitcnt lgkmcnt(0)
	v_add_f32_e32 v66, v78, v140
	v_add_f32_e32 v67, v79, v141
	v_max3_f32 v76, v76, v82, v83
	v_max3_f32 v77, v77, v84, v85
	v_max3_f32 v76, v76, v88, v89
	v_max3_f32 v77, v77, v86, v87
	v_max3_f32 v76, v76, v114, v115
	v_max3_f32 v77, v77, v64, v65
	v_max3_f32 v76, v76, v72, v73
	v_max3_f32 v77, v77, v66, v67
	v_max3_f32 v76, v76, v74, v75
	v_max_f32_e32 v76, v76, v77
	s_nop 0
	v_mov_b32_e32 v77, v76
	s_nop 1
	v_permlane32_swap_b32_e32 v76, v77
	v_max_f32_e32 v76, v76, v77
	s_nop 0
	v_cmp_lt_f32_e32 vcc, s78, v76
	s_cbranch_vccz .LBB0_209
	v_max_f32_e32 v48, v76, v76
	v_max_f32_e32 v48, 0, v48
	v_exp_f32_e64 v49, -v48
	s_and_saveexec_b64 s[38:39], s[4:5]
	ds_write_b32 v132, v49
	s_or_b64 exec, exec, s[38:39]
	s_waitcnt lgkmcnt(0)
	ds_read_b128 v[50:53], v133 offset:64
	ds_read_b128 v[54:57], v133 offset:96
	ds_read_b128 v[58:61], v133
	ds_read_b128 v[76:79], v133 offset:32
	v_add_f32_e32 v131, v131, v48
	v_sub_f32_e32 v63, 0, v131
	v_sub_f32_e32 v112, v112, v48
	v_sub_f32_e32 v113, v113, v48
	v_sub_f32_e32 v108, v108, v48
	v_sub_f32_e32 v109, v109, v48
	v_sub_f32_e32 v80, v80, v48
	v_sub_f32_e32 v81, v81, v48
	v_sub_f32_e32 v68, v68, v48
	v_sub_f32_e32 v69, v69, v48
	v_sub_f32_e32 v88, v88, v48
	v_sub_f32_e32 v89, v89, v48
	v_sub_f32_e32 v84, v84, v48
	v_sub_f32_e32 v85, v85, v48
	v_sub_f32_e32 v72, v72, v48
	v_sub_f32_e32 v73, v73, v48
	v_sub_f32_e32 v64, v64, v48
	v_sub_f32_e32 v65, v65, v48
	v_sub_f32_e32 v116, v116, v48
	v_sub_f32_e32 v117, v117, v48
	v_sub_f32_e32 v110, v110, v48
	v_sub_f32_e32 v111, v111, v48
	v_sub_f32_e32 v82, v82, v48
	v_sub_f32_e32 v83, v83, v48
	v_sub_f32_e32 v70, v70, v48
	v_sub_f32_e32 v71, v71, v48
	v_sub_f32_e32 v114, v114, v48
	v_sub_f32_e32 v115, v115, v48
	v_sub_f32_e32 v86, v86, v48
	v_sub_f32_e32 v87, v87, v48
	v_sub_f32_e32 v74, v74, v48
	v_sub_f32_e32 v75, v75, v48
	v_sub_f32_e32 v66, v66, v48
	v_sub_f32_e32 v67, v67, v48
	v_mul_f32_e32 v125, v125, v49
	s_waitcnt lgkmcnt(2)
	v_pk_mul_f32 v[46:47], v[46:47], v[56:57]
	v_pk_mul_f32 v[42:43], v[42:43], v[52:53]
	s_waitcnt lgkmcnt(0)
	v_pk_mul_f32 v[38:39], v[38:39], v[78:79]
	v_pk_mul_f32 v[34:35], v[34:35], v[60:61]
	v_pk_mul_f32 v[44:45], v[44:45], v[54:55]
	v_pk_mul_f32 v[40:41], v[40:41], v[50:51]
	v_pk_mul_f32 v[36:37], v[36:37], v[76:77]
	v_pk_mul_f32 v[32:33], v[32:33], v[58:59]
	v_pk_mul_f32 v[30:31], v[30:31], v[56:57]
	v_pk_mul_f32 v[26:27], v[26:27], v[52:53]
	v_pk_mul_f32 v[22:23], v[22:23], v[78:79]
	v_pk_mul_f32 v[18:19], v[18:19], v[60:61]
	v_pk_mul_f32 v[28:29], v[28:29], v[54:55]
	v_pk_mul_f32 v[24:25], v[24:25], v[50:51]
	v_pk_mul_f32 v[20:21], v[20:21], v[76:77]
	v_pk_mul_f32 v[16:17], v[16:17], v[58:59]
	v_mov_b32_e32 v62, v63
	v_mov_b32_e32 v61, v63
	v_mov_b32_e32 v60, v63
	v_mov_b32_e32 v59, v63
	v_mov_b32_e32 v58, v63
	v_mov_b32_e32 v57, v63
	v_mov_b32_e32 v56, v63
	v_mov_b32_e32 v55, v63
	v_mov_b32_e32 v54, v63
	v_mov_b32_e32 v53, v63
	v_mov_b32_e32 v52, v63
	v_mov_b32_e32 v51, v63
	v_mov_b32_e32 v50, v63
	v_mov_b32_e32 v49, v63
	v_mov_b32_e32 v48, v63
